# first grid sync via XCD barrier; attention unit index permuted so one XCD takes consecutive key blocks
# speedup vs baseline: 1.0036x; 1.0036x over previous
; __device__ __forceinline__ void xcd_barrier(const XcdBarrier& b) {
;     asm volatile("s_waitcnt vmcnt(0)" ::: "memory");
;     __syncthreads();
;     if (threadIdx.x == 0) {
;         unsigned* bar = b.bar;
;         __builtin_amdgcn_s_waitcnt(0);
;         unsigned nloc = b.st[0], nx = b.st[1];
;         if (nloc == 0u) { xcd_barrier_complete(bar, b.x, nloc, nx); b.st[0] = nloc; b.st[1] = nx; }
.LBB0_55:
	s_or_b64 exec, exec, s[0:1]
	s_xor_b64 s[2:3], s[2:3], -1
	v_writelane_b32 v251, s2, 44
	s_mov_b64 s[0:1], -1
	s_and_b64 vcc, exec, s[2:3]
	v_writelane_b32 v251, s3, 45
	s_movk_i32 s41, 0x1000
	s_nop 0
	s_waitcnt vmcnt(0)
	s_barrier
	s_mov_b64 s[0:1], exec
	v_readlane_b32 s2, v250, 2
	v_readlane_b32 s3, v250, 3
	s_and_b64 s[2:3], s[0:1], s[2:3]
	s_mov_b64 exec, s[2:3]
	s_cbranch_execz .LBB0_108
	v_readlane_b32 s2, v254, 52
	s_waitcnt vmcnt(0) expcnt(0) lgkmcnt(0)
	s_nop 0
	v_mov_b32_e32 v0, s2
	ds_read_b32 v2, v0
	v_readlane_b32 s2, v254, 53
	s_waitcnt lgkmcnt(0)
	v_cmp_ne_u32_e32 vcc, 0, v2
	v_mov_b32_e32 v0, s2
	ds_read_b32 v0, v0
	s_cbranch_vccnz .LBB0_72
	s_mov_b32 s8, 1
	s_branch .LBB0_60

; #define LAS __attribute__((address_space(3)))
; __device__ __forceinline__ int fresh_tid() { int t = threadIdx.x; asm volatile("" : "+v"(t)); return t; }
; #define ATB_LOAD(c_) do { _Pragma("unroll") for (int it = 0; it < 4; ++it) { const size_t t_ = tok0 + (size_t)(c_) * 128 + srr + 32 * it; \
;         kreg[it] = *(const u32x4*)(kbase + t_ * QKVW + sch * 8); vreg[it] = *(const u32x4*)(vbase + t_ * QKVW + sch * 8); } } while (0)
; __device__ __forceinline__ void attn_b_unit(LAS unsigned char* lds, bf16_t* QKV, int unit) {
;     ...
;     const int tid = fresh_tid(), wid = tid >> 6, lane = tid & 63, fr = lane & 15, fq = lane >> 4;
;     const int b = unit >> 9; const int hb = (unit >> 7) & 3; const int n = unit & 127;
;     const size_t tok0 = (size_t)b * SEQ;
;     const bf16_t* kbase = QKV + 5120 + hb * 128; const bf16_t* vbase = QKV + 5632 + hb * 128;
;     const int qi = wid * 16 + fr;
;     const LAS bf16_t* vsw[2] = {Vt + fr * VT_PITCH + 4 * (fq ^ (fr >> 3)), Vt + fr * VT_PITCH + 4 * (fq ^ (2 + (fr >> 3)))};
;     const size_t tq = tok0 + (size_t)n * 128 + qi;
;     bf16x8 qf[4];
; #pragma unroll
;     for (int ds = 0; ds < 4; ++ds) qf[ds] = *(const bf16x8*)(QKV + tq * QKVW + 4608 + hb * 128 + ds * 32 + fq * 8);
;     f32x4 o[8];
; #pragma unroll
;     for (int i = 0; i < 8; ++i) o[i] = (f32x4){0.f, 0.f, 0.f, 0.f};
;     constexpr float LOG2E = 1.4426950408889634f;
;     float after = 0.f;
;     const int dq = qi - 4 * fq;
;     u32x4 kreg[4], vreg[4];
;     const int srr = tid >> 4, sch = tid & 15;
;     ...
;     ATB_LOAD(n);
.LBB0_192:
	s_waitcnt vmcnt(15)
	v_mov_b32_e32 v16, v230
	s_ashr_i32 s0, s3, 9
	s_and_b32 s74, s3, 0x7f
	s_lshr_b32 s4, s74, 3
	s_and_b32 s74, s74, 7
	s_lshl_b32 s74, s74, 4
	s_or_b32 s74, s74, s4
	s_mov_b32 s4, s74
	v_ashrrev_i32_e32 v54, 6, v16
	v_and_b32_e32 v56, 15, v16
	s_ashr_i32 s1, s0, 31
	v_bfe_u32 v57, v16, 4, 2
	s_lshl_b64 s[0:1], s[0:1], 14
	v_lshl_or_b32 v48, v54, 4, v56
	v_bfe_u32 v0, v16, 3, 1
	s_lshl_b32 s4, s4, 7
	v_xor_b32_e32 v1, v57, v0
	v_bitop3_b32 v0, v0, v57, 2 bitop3:0x36
	s_or_b32 s4, s0, s4
	s_mov_b32 s5, s1
	v_ashrrev_i32_e32 v49, 31, v48
	v_lshlrev_b32_e32 v60, 3, v1
	v_lshlrev_b32_e32 v61, 3, v0
	v_lshl_add_u64 v[0:1], s[4:5], 0, v[48:49]
	v_mov_b64_e32 v[2:3], s[82:83]
	v_mad_u64_u32 v[2:3], s[6:7], v0, s86, v[2:3]
	v_readlane_b32 s6, v254, 58
	s_and_b32 s8, s3, 0x180
	v_readlane_b32 s7, v254, 59
	v_mad_i32_i24 v3, v1, s86, v3
	s_mov_b32 s11, s7
	s_lshl_b32 s10, s8, 1
	v_lshl_add_u64 v[0:1], v[2:3], 0, s[10:11]
	s_mov_b64 s[6:7], 0x2400
	v_lshl_add_u64 v[112:113], v[0:1], 0, s[6:7]
	v_readlane_b32 s6, v253, 1
	s_add_u32 s6, s6, s10
	v_readlane_b32 s7, v253, 2
	v_readlane_b32 s8, v252, 63
	s_mov_b32 s9, s11
	s_addc_u32 s7, s7, 0
	v_writelane_b32 v254, s8, 58
	v_ashrrev_i32_e32 v52, 4, v16
	v_ashrrev_i32_e32 v53, 31, v52
	v_writelane_b32 v254, s9, 59
	s_add_u32 s8, s8, s10
	v_readlane_b32 s9, v253, 0
	s_addc_u32 s9, s9, 0
	v_lshlrev_b32_e32 v18, 4, v56
	v_mov_b32_e32 v19, v192
	v_and_b32_e32 v55, 63, v16
	v_and_b32_e32 v50, 48, v16
	v_lshl_add_u64 v[16:17], s[4:5], 0, v[52:53]
	v_lshl_add_u64 v[114:115], s[6:7], 0, v[18:19]
	v_lshl_add_u64 v[116:117], s[8:9], 0, v[18:19]
	s_waitcnt vmcnt(9)
	v_mad_u64_u32 v[40:41], s[4:5], v16, s86, v[114:115]
	v_mad_u64_u32 v[42:43], s[4:5], v16, s86, v[116:117]
	s_mov_b32 s5, 0x60000
	v_mad_i32_i24 v41, v17, s86, v41
	v_add_co_u32_e32 v24, vcc, s5, v40
	v_mad_i32_i24 v43, v17, s86, v43
	s_nop 0
	v_addc_co_u32_e32 v25, vcc, 0, v41, vcc
	v_add_co_u32_e32 v28, vcc, s5, v42
	s_mov_b32 s5, 0xc0000
	s_nop 0
	v_addc_co_u32_e32 v29, vcc, 0, v43, vcc
	v_add_co_u32_e32 v32, vcc, s5, v40
	v_mov_b32_e32 v51, v192
	s_nop 0
	v_addc_co_u32_e32 v33, vcc, 0, v41, vcc
	v_add_co_u32_e32 v36, vcc, s5, v42
	v_lshl_add_u64 v[12:13], v[112:113], 0, v[50:51]
	s_nop 0
	v_addc_co_u32_e32 v37, vcc, 0, v43, vcc
	s_mov_b32 s5, 0x120000
	global_load_dwordx4 v[0:3], v[12:13], off
	global_load_dwordx4 v[4:7], v[12:13], off offset:64
	global_load_dwordx4 v[8:11], v[12:13], off offset:128
	s_nop 0
	global_load_dwordx4 v[12:15], v[12:13], off offset:192
	s_nop 0
	global_load_dwordx4 v[16:19], v[40:41], off
	global_load_dwordx4 v[20:23], v[42:43], off
	v_add_co_u32_e32 v40, vcc, s5, v40
	global_load_dwordx4 v[24:27], v[24:25], off
	s_nop 0
	global_load_dwordx4 v[28:31], v[28:29], off
	v_addc_co_u32_e32 v41, vcc, 0, v41, vcc
	s_waitcnt vmcnt(16)
	v_add_co_u32_e32 v44, vcc, s5, v42
	global_load_dwordx4 v[32:35], v[32:33], off
	s_nop 0
	global_load_dwordx4 v[36:39], v[36:37], off
	v_addc_co_u32_e32 v45, vcc, 0, v43, vcc
	global_load_dwordx4 v[40:43], v[40:41], off
	s_nop 0
	global_load_dwordx4 v[44:47], v[44:45], off
	v_lshl_add_u64 v[118:119], s[0:1], 0, v[52:53]
	v_and_b32_e32 v53, 64, v234
	v_xor_b32_e32 v51, 16, v234
	v_add_u32_e32 v53, 64, v53
	v_cmp_lt_i32_e32 vcc, v51, v53
	v_lshlrev_b32_e32 v154, 2, v57
	v_mad_u32_u24 v59, v56, s85, 0
	v_cndmask_b32_e32 v51, v234, v51, vcc
	v_lshlrev_b32_e32 v156, 2, v51
	v_xor_b32_e32 v51, 32, v234
	v_sub_u32_e32 v155, v48, v154
	v_lshlrev_b32_e32 v48, 8, v56
	v_cmp_lt_i32_e32 vcc, v51, v53
	v_sub_u32_e32 v48, v59, v48
	v_lshlrev_b32_e32 v49, 2, v56
	v_cndmask_b32_e32 v51, v234, v51, vcc
	v_readlane_b32 s0, v254, 54
	v_lshlrev_b32_e32 v157, 2, v51
	v_xor_b32_e32 v51, 1, v57
	v_cmp_eq_u32_e64 s[46:47], 0, v55
	v_lshl_add_u32 v158, v54, 2, s0
	v_xor_b32_e32 v54, v49, v52
	v_mad_u32_u24 v55, v56, s87, v48
	v_cmp_gt_u32_e64 s[40:41], v51, v57
	v_xor_b32_e32 v51, 2, v57
	v_lshl_add_u32 v159, v54, 1, v55
	v_add_u32_e32 v54, 32, v52
	v_cmp_gt_u32_e64 s[42:43], v51, v57
	v_xor_b32_e32 v51, 3, v57
	v_xor_b32_e32 v54, v54, v49
	v_cmp_gt_u32_e64 s[44:45], v51, v57
	v_mul_lo_u32 v51, v52, s85
	v_lshl_add_u32 v160, v54, 1, v55
	v_add_u32_e32 v54, 64, v52
	v_add_u32_e32 v52, 0x60, v52
	v_xor_b32_e32 v54, v54, v49
	v_xor_b32_e32 v49, v52, v49
	v_lshl_add_u32 v162, v49, 1, v55
	v_xor_b32_e32 v49, 8, v234
	v_cmp_lt_i32_e32 vcc, v49, v53
	v_mul_u32_u24_e32 v58, 0x110, v56
	v_add_u32_e32 v50, 0, v50
	v_cndmask_b32_e32 v49, v234, v49, vcc
	v_lshlrev_b32_e32 v163, 2, v49
	v_xor_b32_e32 v49, 4, v234
	v_cmp_lt_i32_e32 vcc, v49, v53
	v_mov_b32_e32 v121, 0
	s_mov_b32 s4, 0
	v_cndmask_b32_e32 v49, v234, v49, vcc
	v_lshlrev_b32_e32 v164, 2, v49
	v_xor_b32_e32 v49, 2, v234
	v_cmp_lt_i32_e32 vcc, v49, v53
	v_lshl_add_u32 v161, v54, 1, v55
	v_add_u32_e32 v167, v48, v51
	v_cndmask_b32_e32 v49, v234, v49, vcc
	v_lshlrev_b32_e32 v165, 2, v49
	v_xor_b32_e32 v49, 1, v234
	v_cmp_lt_i32_e32 vcc, v49, v53
	v_add_u32_e32 v168, v50, v58
	v_add_u32_e32 v169, v59, v60
	v_cndmask_b32_e32 v49, v234, v49, vcc
	v_lshlrev_b32_e32 v166, 2, v49
	v_add_u32_e32 v170, v59, v61
	v_mov_b32_e32 v76, v121
	v_mov_b32_e32 v77, v121
	v_mov_b32_e32 v78, v121
	v_mov_b32_e32 v79, v121
	v_mov_b32_e32 v72, v121
	v_mov_b32_e32 v73, v121
	v_mov_b32_e32 v74, v121
	v_mov_b32_e32 v75, v121
	v_mov_b32_e32 v64, v121
	v_mov_b32_e32 v65, v121
	v_mov_b32_e32 v66, v121
	v_mov_b32_e32 v67, v121
	v_mov_b32_e32 v52, v121
	v_mov_b32_e32 v53, v121
	v_mov_b32_e32 v54, v121
	v_mov_b32_e32 v55, v121
	v_mov_b32_e32 v56, v121
	v_mov_b32_e32 v57, v121
	v_mov_b32_e32 v58, v121
	v_mov_b32_e32 v59, v121
	v_mov_b32_e32 v68, v121
	v_mov_b32_e32 v69, v121
	v_mov_b32_e32 v70, v121
	v_mov_b32_e32 v71, v121
	v_mov_b32_e32 v60, v121
	v_mov_b32_e32 v61, v121
	v_mov_b32_e32 v62, v121
	v_mov_b32_e32 v63, v121
	v_mov_b32_e32 v48, v121
	v_mov_b32_e32 v49, v121
	v_mov_b32_e32 v50, v121
	v_mov_b32_e32 v51, v121
	s_branch .LBB0_194

; #define LAS __attribute__((address_space(3)))
; __device__ __forceinline__ int fresh_tid() { int t = threadIdx.x; asm volatile("" : "+v"(t)); return t; }
; #define ATA_LOAD(c_) do { _Pragma("unroll") for (int it = 0; it < 4; ++it) { const size_t t_ = tok0 + (size_t)((n - 1 + (c_)) * 128 + srr + 32 * it) * d + r; \
;         kreg[it] = *(const u32x4*)(kbase + t_ * QKVW + sch * 8); vreg[it] = *(const u32x4*)(vbase + t_ * QKVW + sch * 8); } } while (0)
; __device__ __forceinline__ void attn_a_unit(LAS unsigned char* lds, bf16_t* QKV, float* LSE, int unit) {
;     ...
;     const int tid = fresh_tid(), wid = tid >> 6, lane = tid & 63, fr = lane & 15, fq = lane >> 4;
;     const int b = unit / 1536; const int rem = unit % 1536; const int hh = rem >> 7; const int w = rem & 127;
;     const int g = hh >> 2, dl = 2 * g, d = 1 << dl, nbl = 7 - dl;
;     const int r = w >> nbl, n = w & ((1 << nbl) - 1);
;     const size_t tok0 = (size_t)b * SEQ;
;     const bf16_t* kbase = QKV + 1536 + hh * 128; const bf16_t* vbase = QKV + 3072 + hh * 128;
;     const int qi = wid * 16 + fr;
;     const LAS bf16_t* vsw[2] = {Vt + fr * VT_PITCH + 4 * (fq ^ (fr >> 3)), Vt + fr * VT_PITCH + 4 * (fq ^ (2 + (fr >> 3)))};
;     const size_t tq = tok0 + (size_t)(n * 128 + qi) * d + r;
;     bf16x8 qf[4];
; #pragma unroll
;     for (int ds = 0; ds < 4; ++ds) qf[ds] = *(const bf16x8*)(QKV + tq * QKVW + hh * 128 + ds * 32 + fq * 8);
;     f32x4 o[8];
; #pragma unroll
;     for (int i = 0; i < 8; ++i) o[i] = (f32x4){0.f, 0.f, 0.f, 0.f};
;     constexpr float LOG2E = 1.4426950408889634f;
;     const float sd2 = exp2f(-8.0f * (float)(hh + 1) / 12.0f) * (float)d * LOG2E;
;     const int dq = qi - 4 * fq;
;     float m_run = -1e30f, l_run = 0.f;
;     u32x4 kreg[4], vreg[4];
;     const int srr = tid >> 4, sch = tid & 15;
;     ...
;     ATA_LOAD(1);
.LBB0_199:
	s_mul_hi_i32 s0, s75, 0x2aaaaaab
	s_lshr_b32 s1, s0, 31
	s_ashr_i32 s0, s0, 8
	s_add_i32 s0, s0, s1
	s_mul_i32 s1, s0, 0x600
	s_sub_i32 s8, s75, s1
	s_ashr_i32 s4, s8, 9
	v_writelane_b32 v251, s75, 48
	s_mov_b32 s2, s4
	v_writelane_b32 v251, s2, 49
	s_waitcnt vmcnt(15)
	v_mov_b32_e32 v16, v230
	s_and_b32 s1, s8, 0x7f
	v_writelane_b32 v251, s3, 50
	s_lshl_b32 s2, s4, 1
	s_lshr_b32 s3, s1, 3
	s_and_b32 s1, s1, 7
	s_lshl_b32 s1, s1, 4
	s_or_b32 s1, s1, s3
	s_sub_i32 s3, 7, s2
	v_ashrrev_i32_e32 v1, 2, v16
	v_lshrrev_b32_e32 v0, 4, v16
	s_lshr_b32 s6, s1, s3
	s_lshl_b32 s3, -1, s3
	v_bfi_b32 v59, -16, v1, v16
	v_bfe_u32 v1, v16, 3, 1
	v_bfe_u32 v101, v16, 4, 2
	s_andn2_b32 s3, s1, s3
	v_bitop3_b32 v0, v0, v1, 3 bitop3:0x6c
	v_lshlrev_b32_e32 v62, 3, v0
	v_bitop3_b32 v0, v1, v101, 2 bitop3:0x36
	s_lshl_b32 s10, s3, 7
	s_ashr_i32 s1, s0, 31
	v_lshlrev_b32_e32 v63, 3, v0
	v_add_u32_e32 v0, s10, v59
	s_lshl_b64 s[0:1], s[0:1], 14
	v_ashrrev_i32_e32 v1, 31, v0
	v_lshlrev_b64 v[0:1], s2, v[0:1]
	s_or_b32 s0, s0, s6
	v_lshl_add_u64 v[80:81], v[0:1], 0, s[0:1]
	v_mov_b64_e32 v[0:1], s[82:83]
	v_mad_u64_u32 v[0:1], s[6:7], v80, s86, v[0:1]
	s_and_b32 s4, s8, 0xffffff80
	v_mov_b32_e32 v2, v1
	s_ashr_i32 s5, s4, 31
	v_mad_u64_u32 v[2:3], s[6:7], v81, s86, v[2:3]
	s_lshl_b64 s[4:5], s[4:5], 1
	v_writelane_b32 v251, s8, 51
	s_ashr_i32 s8, s8, 7
	v_readlane_b32 s6, v253, 7
	s_add_u32 s6, s6, s4
	v_readlane_b32 s7, v253, 8
	v_mov_b32_e32 v1, v2
	s_addc_u32 s7, s7, s5
	s_lshl_b32 s11, 1, s2
	v_readlane_b32 s9, v253, 5
	v_lshl_add_u64 v[82:83], v[0:1], 0, s[4:5]
	s_add_u32 s4, s9, s4
	v_readlane_b32 s9, v253, 6
	s_addc_u32 s5, s9, s5
	s_add_i32 s8, s8, 1
	v_cvt_f32_i32_e32 v0, s8
	s_mov_b32 s12, 0x41400000
	v_ashrrev_i32_e32 v64, 4, v16
	v_add_u32_e32 v50, s10, v64
	v_mul_f32_e32 v17, 0xc1000000, v0
	v_div_scale_f32 v18, s[8:9], s12, s12, v17
	v_rcp_f32_e32 v19, v18
	s_mov_b32 s8, 0xc2fc0000
	s_waitcnt vmcnt(13)
	v_add_u32_e32 v24, 32, v50
	s_waitcnt vmcnt(11)
	v_add_u32_e32 v32, 64, v50
	v_fma_f32 v20, -v18, v19, 1.0
	v_fmac_f32_e32 v19, v20, v19
	v_div_scale_f32 v20, vcc, v17, s12, v17
	v_mul_f32_e32 v21, v20, v19
	v_fma_f32 v22, -v18, v21, v20
	v_fmac_f32_e32 v21, v22, v19
	v_fma_f32 v18, -v18, v21, v20
	v_div_fmas_f32 v18, v18, v19, v21
	v_div_fixup_f32 v17, v18, s12, v17
	v_cmp_gt_f32_e32 vcc, s8, v17
	s_and_b64 s[8:9], vcc, exec
	s_cselect_b32 s8, 0xffffffc0, 0
	v_cndmask_b32_e32 v18, 0, v236, vcc
	v_add_f32_e32 v17, v17, v18
	v_exp_f32_e32 v17, v17
	v_cvt_f32_u32_e32 v18, s11
	s_waitcnt vmcnt(9)
	v_add_u32_e32 v40, 0x60, v50
	v_and_b32_e32 v58, 15, v16
	v_lshlrev_b32_e32 v48, 4, v101
	v_mov_b32_e32 v49, v192
	v_ldexp_f32 v17, v17, s8
	v_ashrrev_i32_e32 v51, 31, v50
	v_ashrrev_i32_e32 v25, 31, v24
	v_ashrrev_i32_e32 v33, 31, v32
	v_ashrrev_i32_e32 v41, 31, v40
	v_lshl_add_u64 v[12:13], v[82:83], 0, v[48:49]
	v_mul_f32_e32 v49, v17, v18
	v_lshlrev_b32_e32 v52, 4, v58
	v_mov_b32_e32 v53, v192
	v_lshlrev_b64 v[16:17], s2, v[50:51]
	v_lshlrev_b64 v[24:25], s2, v[24:25]
	v_lshlrev_b64 v[32:33], s2, v[32:33]
	v_lshlrev_b64 v[40:41], s2, v[40:41]
	v_lshl_add_u64 v[54:55], s[6:7], 0, v[52:53]
	v_lshl_add_u64 v[56:57], s[4:5], 0, v[52:53]
	v_lshl_add_u64 v[16:17], v[16:17], 0, s[0:1]
	v_lshl_add_u64 v[24:25], v[24:25], 0, s[0:1]
	v_lshl_add_u64 v[32:33], v[32:33], 0, s[0:1]
	v_lshl_add_u64 v[40:41], v[40:41], 0, s[0:1]
	global_load_dwordx4 v[0:3], v[12:13], off
	global_load_dwordx4 v[4:7], v[12:13], off offset:64
	global_load_dwordx4 v[8:11], v[12:13], off offset:128
	s_nop 0
	global_load_dwordx4 v[12:15], v[12:13], off offset:192
	v_mad_u64_u32 v[18:19], s[4:5], v16, s86, v[54:55]
	v_mul_lo_u32 v17, v17, s86
	v_mad_u64_u32 v[20:21], s[4:5], v16, s86, v[56:57]
	v_mad_u64_u32 v[26:27], s[4:5], v24, s86, v[54:55]
	v_mul_lo_u32 v25, v25, s86
	v_mad_u64_u32 v[28:29], s[4:5], v24, s86, v[56:57]
	v_mad_u64_u32 v[34:35], s[4:5], v32, s86, v[54:55]
	v_mul_lo_u32 v33, v33, s86
	v_mad_u64_u32 v[36:37], s[4:5], v32, s86, v[56:57]
	v_mad_u64_u32 v[42:43], s[4:5], v40, s86, v[54:55]
	v_mul_lo_u32 v41, v41, s86
	s_waitcnt vmcnt(12)
	v_mad_u64_u32 v[44:45], s[4:5], v40, s86, v[56:57]
	v_add_u32_e32 v19, v17, v19
	v_add_u32_e32 v21, v17, v21
	v_add_u32_e32 v27, v25, v27
	v_add_u32_e32 v29, v25, v29
	v_add_u32_e32 v35, v33, v35
	v_add_u32_e32 v37, v33, v37
	v_add_u32_e32 v43, v41, v43
	v_add_u32_e32 v45, v41, v45
	global_load_dwordx4 v[16:19], v[18:19], off
	s_nop 0
	global_load_dwordx4 v[20:23], v[20:21], off
	s_nop 0
	global_load_dwordx4 v[24:27], v[26:27], off
	s_nop 0
	global_load_dwordx4 v[28:31], v[28:29], off
	s_nop 0
	global_load_dwordx4 v[32:35], v[34:35], off
	s_nop 0
	global_load_dwordx4 v[36:39], v[36:37], off
	s_nop 0
	global_load_dwordx4 v[40:43], v[42:43], off
	s_nop 0
	global_load_dwordx4 v[44:47], v[44:45], off
	s_cmp_eq_u32 s3, 0
	s_cselect_b64 s[4:5], -1, 0
	v_mul_f32_e32 v104, 0x3fb8aa3b, v49
	v_cndmask_b32_e64 v49, 0, 1, s[4:5]
	v_lshlrev_b32_e32 v102, 2, v101
	v_readfirstlane_b32 s76, v49
	v_add_u32_e32 v51, 0, v52
	v_lshlrev_b32_e32 v49, 2, v58
	v_and_b32_e32 v53, 64, v234
	v_mul_u32_u24_e32 v60, 0x110, v58
	v_mad_u32_u24 v61, v58, s85, 0
	v_sub_u32_e32 v105, v59, v102
	v_add_u32_e32 v52, 0, v48
	v_xor_b32_e32 v48, 16, v234
	v_add_u32_e32 v53, 64, v53
	v_xor_b32_e32 v59, v49, v64
	v_mad_u32_u24 v58, v58, s87, v51
	v_cmp_lt_i32_e32 vcc, v48, v53
	v_lshl_add_u32 v108, v59, 1, v58
	v_add_u32_e32 v59, 32, v64
	v_cndmask_b32_e32 v48, v234, v48, vcc
	v_xor_b32_e32 v59, v59, v49
	v_lshlrev_b32_e32 v106, 2, v48
	v_xor_b32_e32 v48, 32, v234
	v_lshl_add_u32 v109, v59, 1, v58
	v_add_u32_e32 v59, 64, v64
	v_cmp_lt_i32_e32 vcc, v48, v53
	v_xor_b32_e32 v59, v59, v49
; #define LAS __attribute__((address_space(3)))
; #define ATA_LOAD(c_) do { _Pragma("unroll") for (int it = 0; it < 4; ++it) { const size_t t_ = tok0 + (size_t)((n - 1 + (c_)) * 128 + srr + 32 * it) * d + r; \
;         kreg[it] = *(const u32x4*)(kbase + t_ * QKVW + sch * 8); vreg[it] = *(const u32x4*)(vbase + t_ * QKVW + sch * 8); } } while (0)
; __device__ __forceinline__ void attn_a_unit(LAS unsigned char* lds, bf16_t* QKV, float* LSE, int unit) {
;     ...
;     const int qi = wid * 16 + fr;
;     const LAS bf16_t* vsw[2] = {Vt + fr * VT_PITCH + 4 * (fq ^ (fr >> 3)), Vt + fr * VT_PITCH + 4 * (fq ^ (2 + (fr >> 3)))};
;     const size_t tq = tok0 + (size_t)(n * 128 + qi) * d + r;
;     bf16x8 qf[4];
; #pragma unroll
;     for (int ds = 0; ds < 4; ++ds) qf[ds] = *(const bf16x8*)(QKV + tq * QKVW + hh * 128 + ds * 32 + fq * 8);
;     f32x4 o[8];
; #pragma unroll
;     for (int i = 0; i < 8; ++i) o[i] = (f32x4){0.f, 0.f, 0.f, 0.f};
;     constexpr float LOG2E = 1.4426950408889634f;
;     const float sd2 = exp2f(-8.0f * (float)(hh + 1) / 12.0f) * (float)d * LOG2E;
;     const int dq = qi - 4 * fq;
;     float m_run = -1e30f, l_run = 0.f;
;     u32x4 kreg[4], vreg[4];
;     const int srr = tid >> 4, sch = tid & 15;
;     ...
;     ATA_LOAD(1);
;     const int cmin = (n > 0) ? 0 : 1;
	v_lshl_add_u32 v110, v59, 1, v58
	v_cndmask_b32_e32 v48, v234, v48, vcc
	v_add_u32_e32 v59, 0x60, v64
	v_lshlrev_b32_e32 v107, 2, v48
	v_add_u32_e32 v48, 0xffffff80, v50
	v_xor_b32_e32 v49, v59, v49
	v_lshl_add_u32 v111, v49, 1, v58
	v_ashrrev_i32_e32 v49, 31, v48
	v_lshlrev_b64 v[48:49], s2, v[48:49]
	v_lshl_add_u64 v[48:49], v[48:49], 0, s[0:1]
	v_mad_u64_u32 v[84:85], s[4:5], v48, s86, v[54:55]
	v_mul_lo_u32 v49, v49, s86
	v_mad_u64_u32 v[86:87], s[4:5], v48, s86, v[56:57]
	v_add_u32_e32 v48, 0xffffffa0, v50
	v_add_u32_e32 v85, v49, v85
	v_add_u32_e32 v87, v49, v87
	v_ashrrev_i32_e32 v49, 31, v48
	v_lshlrev_b64 v[48:49], s2, v[48:49]
	v_lshl_add_u64 v[48:49], v[48:49], 0, s[0:1]
	v_mad_u64_u32 v[88:89], s[4:5], v48, s86, v[54:55]
	v_mul_lo_u32 v49, v49, s86
	v_mad_u64_u32 v[90:91], s[4:5], v48, s86, v[56:57]
	v_subrev_u32_e32 v48, 64, v50
	v_add_u32_e32 v89, v49, v89
	v_add_u32_e32 v91, v49, v91
	v_ashrrev_i32_e32 v49, 31, v48
	v_lshlrev_b64 v[48:49], s2, v[48:49]
	v_lshl_add_u64 v[48:49], v[48:49], 0, s[0:1]
	v_mad_u64_u32 v[92:93], s[4:5], v48, s86, v[54:55]
	v_mul_lo_u32 v49, v49, s86
	v_mad_u64_u32 v[94:95], s[4:5], v48, s86, v[56:57]
	v_subrev_u32_e32 v48, 32, v50
	v_add_u32_e32 v93, v49, v93
	v_add_u32_e32 v95, v49, v95
	v_ashrrev_i32_e32 v49, 31, v48
	v_lshlrev_b64 v[48:49], s2, v[48:49]
	v_lshl_add_u64 v[48:49], v[48:49], 0, s[0:1]
	v_mad_u64_u32 v[96:97], s[0:1], v48, s86, v[54:55]
	v_mad_u64_u32 v[98:99], s[0:1], v48, s86, v[56:57]
	v_cmp_lt_i32_e64 s[0:1], -1, v105
	s_movk_i32 s2, 0x51
	v_cmp_gt_i32_e64 s[38:39], s2, v105
	v_writelane_b32 v251, s0, 52
	v_cmp_lt_i32_e64 s[42:43], s2, v105
	s_movk_i32 s2, 0x53
	v_writelane_b32 v251, s1, 53
	v_cmp_gt_i32_e64 s[0:1], 1, v105
	s_movk_i32 s3, 0x52
	v_cmp_gt_i32_e64 s[44:45], s2, v105
	v_writelane_b32 v251, s0, 54
	s_movk_i32 s2, 0x60
	v_cmp_gt_i32_e64 s[40:41], s3, v105
	v_writelane_b32 v251, s1, 55
	v_cmp_lt_i32_e64 s[0:1], 0, v105
	v_cmp_lt_i32_e64 s[46:47], s3, v105
	s_movk_i32 s3, 0x61
	v_writelane_b32 v251, s0, 56
	v_cmp_lt_i32_e64 s[50:51], s2, v105
	s_movk_i32 s2, 0x63
	v_writelane_b32 v251, s1, 57
	v_cmp_gt_i32_e64 s[0:1], 2, v105
	v_cmp_gt_i32_e64 s[48:49], s3, v105
	v_cmp_lt_i32_e64 s[54:55], s3, v105
	v_writelane_b32 v251, s0, 58
	v_cmp_gt_i32_e64 s[56:57], s2, v105
	s_movk_i32 s3, 0x71
	v_writelane_b32 v251, s1, 59
	v_cmp_lt_i32_e64 s[0:1], 1, v105
	s_movk_i32 s2, 0x70
	v_mov_b32_e32 v103, 0
	v_writelane_b32 v251, s0, 60
	v_mul_lo_u32 v53, v64, s85
	v_mul_lo_u32 v49, v49, s86
	v_writelane_b32 v251, s1, 61
	v_cmp_gt_i32_e64 s[0:1], 3, v105
	s_movk_i32 s58, 0x62
	v_cmp_gt_i32_e64 s[60:61], s3, v105
	v_writelane_b32 v251, s0, 62
	v_cmp_lt_i32_e64 s[62:63], s2, v105
	s_movk_i32 s2, 0x72
	v_writelane_b32 v251, s1, 63
	v_cmp_lt_i32_e64 s[0:1], 2, v105
	v_cmp_lt_i32_e64 s[66:67], s3, v105
	s_movk_i32 s3, 0x73
	v_writelane_b32 v255, s0, 0
	s_mov_b32 s33, 1
	v_add_u32_e32 v97, v49, v97
	v_writelane_b32 v255, s1, 1
	v_cmp_gt_i32_e64 s[0:1], 4, v105
	v_add_u32_e32 v99, v49, v99
	v_cmp_gt_i32_e64 s[78:79], 34, v105
	v_writelane_b32 v255, s0, 2
	v_cmp_lt_i32_e64 s[80:81], 33, v105
	v_cmp_gt_i32_e64 s[82:83], 35, v105
	v_writelane_b32 v255, s1, 3
	v_cmp_lt_i32_e64 s[0:1], 15, v105
	v_cmp_lt_i32_e64 s[84:85], 34, v105
	v_cmp_gt_i32_e64 s[86:87], 36, v105
	v_writelane_b32 v255, s0, 4
	v_cmp_lt_i32_e64 s[88:89], 47, v105
	v_mov_b32_e32 v100, 0xf149f2ca
	v_writelane_b32 v255, s1, 5
	v_cmp_gt_i32_e64 s[0:1], 17, v105
	v_add_u32_e32 v112, v51, v53
	v_add_u32_e32 v113, v52, v60
	v_writelane_b32 v255, s0, 6
	v_add_u32_e32 v114, v61, v62
	v_add_u32_e32 v115, v61, v63
	v_writelane_b32 v255, s1, 7
	v_cmp_lt_i32_e64 s[0:1], 16, v105
	v_mov_b32_e32 v48, 0
	v_mov_b32_e32 v49, v103
	v_writelane_b32 v255, s0, 8
	v_mov_b32_e32 v50, v103
	v_mov_b32_e32 v51, v103
	v_writelane_b32 v255, s1, 9
	v_cmp_gt_i32_e64 s[0:1], 18, v105
	v_mov_b32_e32 v52, 0
	v_mov_b32_e32 v53, v103
	v_writelane_b32 v255, s0, 10
	v_mov_b32_e32 v54, v103
	v_mov_b32_e32 v55, v103
	v_writelane_b32 v255, s1, 11
	v_cmp_lt_i32_e64 s[0:1], 17, v105
	v_mov_b32_e32 v56, 0
	v_mov_b32_e32 v57, v103
	v_writelane_b32 v255, s0, 12
	v_mov_b32_e32 v58, v103
	v_mov_b32_e32 v59, v103
	v_writelane_b32 v255, s1, 13
	v_cmp_gt_i32_e64 s[0:1], 19, v105
	v_mov_b32_e32 v60, 0
	v_mov_b32_e32 v61, v103
	v_writelane_b32 v255, s0, 14
	v_mov_b32_e32 v62, v103
	v_mov_b32_e32 v63, v103
	v_writelane_b32 v255, s1, 15
	v_cmp_lt_i32_e64 s[0:1], 18, v105
	v_mov_b32_e32 v64, 0
	v_mov_b32_e32 v65, v103
	v_writelane_b32 v255, s0, 16
	v_mov_b32_e32 v66, v103
	v_mov_b32_e32 v67, v103
	v_writelane_b32 v255, s1, 17
	v_cmp_gt_i32_e64 s[0:1], 20, v105
	v_mov_b32_e32 v68, 0
	v_mov_b32_e32 v69, v103
	v_writelane_b32 v255, s0, 18
	v_mov_b32_e32 v70, v103
	v_mov_b32_e32 v71, v103
	v_writelane_b32 v255, s1, 19
	v_cmp_lt_i32_e64 s[0:1], 31, v105
	v_mov_b32_e32 v72, 0
	v_mov_b32_e32 v73, v103
	v_writelane_b32 v255, s0, 20
	v_mov_b32_e32 v74, v103
	v_mov_b32_e32 v75, v103
	v_writelane_b32 v255, s1, 21
	v_cmp_gt_i32_e64 s[0:1], 33, v105
	v_mov_b32_e32 v76, 0
	v_mov_b32_e32 v77, v103
	v_writelane_b32 v255, s0, 22
	v_mov_b32_e32 v78, v103
	v_mov_b32_e32 v79, v103
	v_writelane_b32 v255, s1, 23
	v_cmp_lt_i32_e64 s[0:1], 32, v105
	v_cmp_gt_i32_e64 s[6:7], 49, v105
	v_cmp_lt_i32_e64 s[8:9], 48, v105
	v_writelane_b32 v255, s0, 24
	v_cmp_gt_i32_e64 s[10:11], 50, v105
	v_cmp_lt_i32_e64 s[12:13], 49, v105
	v_writelane_b32 v255, s1, 25
	s_movk_i32 s0, 0x44
	v_cmp_gt_i32_e64 s[90:91], s0, v105
	s_movk_i32 s0, 0x4f
	v_cmp_lt_i32_e64 s[92:93], s0, v105
	s_movk_i32 s0, 0x54
	v_cmp_gt_i32_e64 s[94:95], s0, v105
	s_movk_i32 s0, 0x5f
	v_cmp_lt_i32_e64 s[96:97], s0, v105
	s_movk_i32 s0, 0x64
	v_cmp_gt_i32_e64 s[36:37], s0, v105
	s_movk_i32 s0, 0x6f
	v_cmp_lt_i32_e64 s[72:73], s0, v105
	s_movk_i32 s0, 0x74
	v_cmp_gt_i32_e64 s[4:5], s0, v105
	s_movk_i32 s0, 0x41
	v_cmp_gt_i32_e64 s[22:23], s0, v105
	v_cmp_lt_i32_e64 s[28:29], s0, v105
	s_movk_i32 s0, 0x43
	s_movk_i32 s1, 0x42
	v_cmp_gt_i32_e64 s[30:31], s0, v105
	s_movk_i32 s0, 0x50
	v_cmp_gt_i32_e64 s[14:15], 51, v105
	v_cmp_lt_i32_e64 s[16:17], 50, v105
	v_cmp_gt_i32_e64 s[18:19], 52, v105
	v_cmp_lt_i32_e64 s[20:21], 63, v105
	v_cmp_lt_i32_e64 s[24:25], 64, v105
	v_cmp_gt_i32_e64 s[26:27], s1, v105
	v_cmp_lt_i32_e64 s[34:35], s1, v105
	v_cmp_lt_i32_e64 s[0:1], s0, v105
	v_cmp_gt_i32_e64 s[52:53], s58, v105
	v_cmp_lt_i32_e64 s[58:59], s58, v105
	v_cmp_gt_i32_e64 s[64:65], s2, v105
	v_cmp_gt_i32_e64 s[68:69], s3, v105
	v_cmp_lt_i32_e64 s[70:71], s2, v105
